# layer-0 gate-weight rows converted in phase 0 again (layer-0 slot back to 8 tiles); layer-1 gate rows still offloaded
# baseline (speedup 1.0000x reference)
.LBB0_241:
	s_or_b64 exec, exec, s[0:1]
	v_readlane_b32 s2, v253, 26
	v_readlane_b32 s3, v253, 27
	s_mov_b64 s[0:1], 0
	s_andn2_b64 vcc, exec, s[2:3]
	s_waitcnt lgkmcnt(0)
	s_barrier
	s_cbranch_vccnz .LBB0_243
	v_lshrrev_b32_e32 v120, 4, v197
	v_and_b32_e32 v121, 15, v197
	v_lshlrev_b32_e32 v121, 2, v121
	v_lshl_add_u32 v122, v120, 10, v121
	v_lshlrev_b32_e32 v122, 2, v122
	v_mul_u32_u24_e32 v138, 0x8800, v120
	v_lshl_add_u32 v138, v121, 2, v138
	v_mul_u32_u24_e32 v123, 0x41, v120
	v_add_u32_e32 v123, v123, v121
	v_lshlrev_b32_e32 v123, 2, v123
	v_lshrrev_b32_e32 v124, 3, v197
	v_and_b32_e32 v125, 7, v197
	v_lshlrev_b32_e32 v125, 3, v125
	v_bfe_u32 v127, v124, 2, 2
	v_lshlrev_b32_e32 v127, 3, v127
	v_bfe_u32 v136, v124, 4, 1
	v_lshl_add_u32 v127, v136, 2, v127
	v_and_b32_e32 v136, 3, v124
	v_add_u32_e32 v127, v127, v136
	v_and_b32_e32 v136, 32, v124
	v_add_u32_e32 v127, v127, v136
	v_mul_u32_u24_e32 v136, 0x41, v125
	v_add_u32_e32 v136, v136, v127
	v_lshlrev_b32_e32 v136, 2, v136
	v_lshl_add_u32 v137, v124, 10, v125
	v_lshlrev_b32_e32 v137, 1, v137
	s_sub_i32 s2, s52, 0x80
	v_readlane_b32 s3, v252, 23
	s_nop 3
	s_cmp_eq_u32 s3, 0
	s_cbranch_scc1 .Lcw_l1
	v_readlane_b32 s28, v253, 4
	v_readlane_b32 s29, v253, 5
	v_readlane_b32 s30, v253, 6
	v_readlane_b32 s31, v253, 7
	s_nop 3
	s_add_i32 s4, s2, 0
	s_cmpk_lt_u32 s4, 0x200
	s_cselect_b32 s6, s28, s30
	s_cselect_b32 s7, s29, s31
	s_mov_b32 s16, 0x10500000
	s_cselect_b32 s16, 0x10100000, s16
	s_bfe_u32 s5, s4, 0x10008
	s_lshl_b32 s3, s5, 22
	s_add_u32 s6, s6, s3
	s_addc_u32 s7, s7, 0
	s_lshl_b32 s3, s5, 21
	s_add_i32 s16, s16, s3
	s_and_b32 s3, s4, 15
	s_bfe_u32 s5, s4, 0x40004
	s_lshl_b32 s17, s3, 18
	s_lshl_b32 s20, s5, 8
	s_add_i32 s17, s17, s20
	s_add_u32 s6, s6, s17
	s_addc_u32 s7, s7, 0
	s_add_u32 s12, s6, 0x20000
	s_addc_u32 s13, s7, 0
	s_lshl_b32 s17, s5, 17
	s_lshl_b32 s20, s3, 7
	s_add_i32 s17, s17, s20
	s_add_i32 s16, s16, s17
	s_add_u32 s16, s96, s16
	s_addc_u32 s17, s97, 0
	global_load_dwordx4 v[140:143], v122, s[6:7]
	global_load_dwordx4 v[150:153], v122, s[12:13]
	s_waitcnt vmcnt(0)
	ds_write_b32 v123, v140 offset:0
	ds_write_b32 v123, v141 offset:4
	ds_write_b32 v123, v142 offset:8
	ds_write_b32 v123, v143 offset:12
	ds_write_b32 v123, v150 offset:8320
	ds_write_b32 v123, v151 offset:8324
	ds_write_b32 v123, v152 offset:8328
	ds_write_b32 v123, v153 offset:8332
	s_waitcnt lgkmcnt(0)
	s_barrier
	s_mov_b64 s[26:27], s[16:17]
	s_add_i32 s4, s2, 128
	s_cmpk_lt_u32 s4, 0x200
	s_cselect_b32 s6, s28, s30
	s_cselect_b32 s7, s29, s31
	s_mov_b32 s16, 0x10500000
	s_cselect_b32 s16, 0x10100000, s16
	s_bfe_u32 s5, s4, 0x10008
	s_lshl_b32 s3, s5, 22
	s_add_u32 s6, s6, s3
	s_addc_u32 s7, s7, 0
	s_lshl_b32 s3, s5, 21
	s_add_i32 s16, s16, s3
	s_and_b32 s3, s4, 15
	s_bfe_u32 s5, s4, 0x40004
	s_lshl_b32 s17, s3, 18
	s_lshl_b32 s20, s5, 8
	s_add_i32 s17, s17, s20
	s_add_u32 s6, s6, s17
	s_addc_u32 s7, s7, 0
	s_add_u32 s12, s6, 0x20000
	s_addc_u32 s13, s7, 0
	s_lshl_b32 s17, s5, 17
	s_lshl_b32 s20, s3, 7
	s_add_i32 s17, s17, s20
	s_add_i32 s16, s16, s17
	s_add_u32 s16, s96, s16
	s_addc_u32 s17, s97, 0
	global_load_dwordx4 v[140:143], v122, s[6:7]
	global_load_dwordx4 v[150:153], v122, s[12:13]
	ds_read_b32 v154, v136 offset:0
	ds_read_b32 v155, v136 offset:260
	ds_read_b32 v156, v136 offset:520
	ds_read_b32 v157, v136 offset:780
	ds_read_b32 v158, v136 offset:1040
	ds_read_b32 v159, v136 offset:1300
	ds_read_b32 v160, v136 offset:1560
	ds_read_b32 v161, v136 offset:1820
	s_waitcnt lgkmcnt(0)
	v_cvt_pk_bf16_f32 v204, v154, v155
	v_cvt_pk_bf16_f32 v205, v156, v157
	v_cvt_pk_bf16_f32 v206, v158, v159
	v_cvt_pk_bf16_f32 v207, v160, v161
	global_store_dwordx4 v137, v[204:207], s[26:27]
	s_barrier
	s_waitcnt vmcnt(0)
	ds_write_b32 v123, v140 offset:0
	ds_write_b32 v123, v141 offset:4
	ds_write_b32 v123, v142 offset:8
	ds_write_b32 v123, v143 offset:12
	ds_write_b32 v123, v150 offset:8320
	ds_write_b32 v123, v151 offset:8324
	ds_write_b32 v123, v152 offset:8328
	ds_write_b32 v123, v153 offset:8332
	s_waitcnt lgkmcnt(0)
	s_barrier
	s_mov_b64 s[26:27], s[16:17]
	s_add_i32 s4, s2, 256
	s_cmpk_lt_u32 s4, 0x200
	s_cselect_b32 s6, s28, s30
	s_cselect_b32 s7, s29, s31
	s_mov_b32 s16, 0x10500000
	s_cselect_b32 s16, 0x10100000, s16
	s_bfe_u32 s5, s4, 0x10008
	s_lshl_b32 s3, s5, 22
	s_add_u32 s6, s6, s3
	s_addc_u32 s7, s7, 0
	s_lshl_b32 s3, s5, 21
	s_add_i32 s16, s16, s3
	s_and_b32 s3, s4, 15
	s_bfe_u32 s5, s4, 0x40004
	s_lshl_b32 s17, s3, 18
	s_lshl_b32 s20, s5, 8
	s_add_i32 s17, s17, s20
	s_add_u32 s6, s6, s17
	s_addc_u32 s7, s7, 0
	s_add_u32 s12, s6, 0x20000
	s_addc_u32 s13, s7, 0
	s_lshl_b32 s17, s5, 17
	s_lshl_b32 s20, s3, 7
	s_add_i32 s17, s17, s20
	s_add_i32 s16, s16, s17
	s_add_u32 s16, s96, s16
	s_addc_u32 s17, s97, 0
	global_load_dwordx4 v[140:143], v122, s[6:7]
	global_load_dwordx4 v[150:153], v122, s[12:13]
	ds_read_b32 v154, v136 offset:0
	ds_read_b32 v155, v136 offset:260
	ds_read_b32 v156, v136 offset:520
	ds_read_b32 v157, v136 offset:780
	ds_read_b32 v158, v136 offset:1040
	ds_read_b32 v159, v136 offset:1300
	ds_read_b32 v160, v136 offset:1560
	ds_read_b32 v161, v136 offset:1820
	s_waitcnt lgkmcnt(0)
	v_cvt_pk_bf16_f32 v204, v154, v155
	v_cvt_pk_bf16_f32 v205, v156, v157
	v_cvt_pk_bf16_f32 v206, v158, v159
	v_cvt_pk_bf16_f32 v207, v160, v161
	global_store_dwordx4 v137, v[204:207], s[26:27]
	s_barrier
	s_waitcnt vmcnt(0)
	ds_write_b32 v123, v140 offset:0
	ds_write_b32 v123, v141 offset:4
	ds_write_b32 v123, v142 offset:8
	ds_write_b32 v123, v143 offset:12
	ds_write_b32 v123, v150 offset:8320
	ds_write_b32 v123, v151 offset:8324
	ds_write_b32 v123, v152 offset:8328
	ds_write_b32 v123, v153 offset:8332
	s_waitcnt lgkmcnt(0)
	s_barrier
	s_mov_b64 s[26:27], s[16:17]
	s_add_i32 s4, s2, 384
	s_cmpk_lt_u32 s4, 0x200
	s_cselect_b32 s6, s28, s30
	s_cselect_b32 s7, s29, s31
	s_mov_b32 s16, 0x10500000
	s_cselect_b32 s16, 0x10100000, s16
	s_bfe_u32 s5, s4, 0x10008
	s_lshl_b32 s3, s5, 22
	s_add_u32 s6, s6, s3
	s_addc_u32 s7, s7, 0
	s_lshl_b32 s3, s5, 21
	s_add_i32 s16, s16, s3
	s_and_b32 s3, s4, 15
	s_bfe_u32 s5, s4, 0x40004
	s_lshl_b32 s17, s3, 18
	s_lshl_b32 s20, s5, 8
	s_add_i32 s17, s17, s20
	s_add_u32 s6, s6, s17
	s_addc_u32 s7, s7, 0
	s_add_u32 s12, s6, 0x20000
	s_addc_u32 s13, s7, 0
	s_lshl_b32 s17, s5, 17
	s_lshl_b32 s20, s3, 7
	s_add_i32 s17, s17, s20
	s_add_i32 s16, s16, s17
	s_add_u32 s16, s96, s16
	s_addc_u32 s17, s97, 0
	global_load_dwordx4 v[140:143], v122, s[6:7]
	global_load_dwordx4 v[150:153], v122, s[12:13]
	ds_read_b32 v154, v136 offset:0
	ds_read_b32 v155, v136 offset:260
	ds_read_b32 v156, v136 offset:520
	ds_read_b32 v157, v136 offset:780
	ds_read_b32 v158, v136 offset:1040
	ds_read_b32 v159, v136 offset:1300
	ds_read_b32 v160, v136 offset:1560
	ds_read_b32 v161, v136 offset:1820
	s_waitcnt lgkmcnt(0)
	v_cvt_pk_bf16_f32 v204, v154, v155
	v_cvt_pk_bf16_f32 v205, v156, v157
	v_cvt_pk_bf16_f32 v206, v158, v159
	v_cvt_pk_bf16_f32 v207, v160, v161
	global_store_dwordx4 v137, v[204:207], s[26:27]
	s_barrier
	s_waitcnt vmcnt(0)
	ds_write_b32 v123, v140 offset:0
	ds_write_b32 v123, v141 offset:4
	ds_write_b32 v123, v142 offset:8
	ds_write_b32 v123, v143 offset:12
	ds_write_b32 v123, v150 offset:8320
	ds_write_b32 v123, v151 offset:8324
	ds_write_b32 v123, v152 offset:8328
	ds_write_b32 v123, v153 offset:8332
	s_waitcnt lgkmcnt(0)
	s_barrier
	s_mov_b64 s[26:27], s[16:17]
	s_add_i32 s4, s2, 512
	s_cmpk_lt_u32 s4, 0x200
	s_cselect_b32 s6, s28, s30
	s_cselect_b32 s7, s29, s31
	s_mov_b32 s16, 0x10500000
	s_cselect_b32 s16, 0x10100000, s16
	s_bfe_u32 s5, s4, 0x10008
	s_lshl_b32 s3, s5, 22
	s_add_u32 s6, s6, s3
	s_addc_u32 s7, s7, 0
	s_lshl_b32 s3, s5, 21
	s_add_i32 s16, s16, s3
	s_and_b32 s3, s4, 15
	s_bfe_u32 s5, s4, 0x40004
	s_lshl_b32 s17, s3, 18
	s_lshl_b32 s20, s5, 8
	s_add_i32 s17, s17, s20
	s_add_u32 s6, s6, s17
	s_addc_u32 s7, s7, 0
	s_add_u32 s12, s6, 0x20000
	s_addc_u32 s13, s7, 0
	s_lshl_b32 s17, s5, 17
	s_lshl_b32 s20, s3, 7
	s_add_i32 s17, s17, s20
	s_add_i32 s16, s16, s17
	s_add_u32 s16, s96, s16
	s_addc_u32 s17, s97, 0
	global_load_dwordx4 v[140:143], v122, s[6:7]
	global_load_dwordx4 v[150:153], v122, s[12:13]
	ds_read_b32 v154, v136 offset:0
	ds_read_b32 v155, v136 offset:260
	ds_read_b32 v156, v136 offset:520
	ds_read_b32 v157, v136 offset:780
	ds_read_b32 v158, v136 offset:1040
	ds_read_b32 v159, v136 offset:1300
	ds_read_b32 v160, v136 offset:1560
	ds_read_b32 v161, v136 offset:1820
	s_waitcnt lgkmcnt(0)
	v_cvt_pk_bf16_f32 v204, v154, v155
	v_cvt_pk_bf16_f32 v205, v156, v157
	v_cvt_pk_bf16_f32 v206, v158, v159
	v_cvt_pk_bf16_f32 v207, v160, v161
	global_store_dwordx4 v137, v[204:207], s[26:27]
	s_barrier
	s_waitcnt vmcnt(0)
	ds_write_b32 v123, v140 offset:0
	ds_write_b32 v123, v141 offset:4
	ds_write_b32 v123, v142 offset:8
	ds_write_b32 v123, v143 offset:12
	ds_write_b32 v123, v150 offset:8320
	ds_write_b32 v123, v151 offset:8324
	ds_write_b32 v123, v152 offset:8328
	ds_write_b32 v123, v153 offset:8332
	s_waitcnt lgkmcnt(0)
	s_barrier
	s_mov_b64 s[26:27], s[16:17]
	s_add_i32 s4, s2, 640
	s_cmpk_lt_u32 s4, 0x200
	s_cselect_b32 s6, s28, s30
	s_cselect_b32 s7, s29, s31
	s_mov_b32 s16, 0x10500000
	s_cselect_b32 s16, 0x10100000, s16
	s_bfe_u32 s5, s4, 0x10008
	s_lshl_b32 s3, s5, 22
	s_add_u32 s6, s6, s3
	s_addc_u32 s7, s7, 0
	s_lshl_b32 s3, s5, 21
	s_add_i32 s16, s16, s3
	s_and_b32 s3, s4, 15
	s_bfe_u32 s5, s4, 0x40004
	s_lshl_b32 s17, s3, 18
	s_lshl_b32 s20, s5, 8
	s_add_i32 s17, s17, s20
	s_add_u32 s6, s6, s17
	s_addc_u32 s7, s7, 0
	s_add_u32 s12, s6, 0x20000
	s_addc_u32 s13, s7, 0
	s_lshl_b32 s17, s5, 17
	s_lshl_b32 s20, s3, 7
	s_add_i32 s17, s17, s20
	s_add_i32 s16, s16, s17
	s_add_u32 s16, s96, s16
	s_addc_u32 s17, s97, 0
	global_load_dwordx4 v[140:143], v122, s[6:7]
	global_load_dwordx4 v[150:153], v122, s[12:13]
	ds_read_b32 v154, v136 offset:0
	ds_read_b32 v155, v136 offset:260
	ds_read_b32 v156, v136 offset:520
	ds_read_b32 v157, v136 offset:780
	ds_read_b32 v158, v136 offset:1040
	ds_read_b32 v159, v136 offset:1300
	ds_read_b32 v160, v136 offset:1560
	ds_read_b32 v161, v136 offset:1820
	s_waitcnt lgkmcnt(0)
	v_cvt_pk_bf16_f32 v204, v154, v155
	v_cvt_pk_bf16_f32 v205, v156, v157
	v_cvt_pk_bf16_f32 v206, v158, v159
	v_cvt_pk_bf16_f32 v207, v160, v161
	global_store_dwordx4 v137, v[204:207], s[26:27]
	s_barrier
	s_waitcnt vmcnt(0)
	ds_write_b32 v123, v140 offset:0
	ds_write_b32 v123, v141 offset:4
	ds_write_b32 v123, v142 offset:8
	ds_write_b32 v123, v143 offset:12
	ds_write_b32 v123, v150 offset:8320
	ds_write_b32 v123, v151 offset:8324
	ds_write_b32 v123, v152 offset:8328
	ds_write_b32 v123, v153 offset:8332
	s_waitcnt lgkmcnt(0)
	s_barrier
	s_mov_b64 s[26:27], s[16:17]
	s_add_i32 s4, s2, 768
	s_cmpk_lt_u32 s4, 0x200
	s_cselect_b32 s6, s28, s30
	s_cselect_b32 s7, s29, s31
	s_mov_b32 s16, 0x10500000
	s_cselect_b32 s16, 0x10100000, s16
	s_bfe_u32 s5, s4, 0x10008
	s_lshl_b32 s3, s5, 22
	s_add_u32 s6, s6, s3
	s_addc_u32 s7, s7, 0
	s_lshl_b32 s3, s5, 21
	s_add_i32 s16, s16, s3
	s_and_b32 s3, s4, 15
	s_bfe_u32 s5, s4, 0x40004
	s_lshl_b32 s17, s3, 18
	s_lshl_b32 s20, s5, 8
	s_add_i32 s17, s17, s20
	s_add_u32 s6, s6, s17
	s_addc_u32 s7, s7, 0
	s_add_u32 s12, s6, 0x20000
	s_addc_u32 s13, s7, 0
	s_lshl_b32 s17, s5, 17
	s_lshl_b32 s20, s3, 7
	s_add_i32 s17, s17, s20
	s_add_i32 s16, s16, s17
	s_add_u32 s16, s96, s16
	s_addc_u32 s17, s97, 0
	global_load_dwordx4 v[140:143], v122, s[6:7]
	global_load_dwordx4 v[150:153], v122, s[12:13]
	ds_read_b32 v154, v136 offset:0
	ds_read_b32 v155, v136 offset:260
	ds_read_b32 v156, v136 offset:520
	ds_read_b32 v157, v136 offset:780
	ds_read_b32 v158, v136 offset:1040
	ds_read_b32 v159, v136 offset:1300
	ds_read_b32 v160, v136 offset:1560
	ds_read_b32 v161, v136 offset:1820
	s_waitcnt lgkmcnt(0)
	v_cvt_pk_bf16_f32 v204, v154, v155
	v_cvt_pk_bf16_f32 v205, v156, v157
	v_cvt_pk_bf16_f32 v206, v158, v159
	v_cvt_pk_bf16_f32 v207, v160, v161
	global_store_dwordx4 v137, v[204:207], s[26:27]
	s_barrier
	s_waitcnt vmcnt(0)
	ds_write_b32 v123, v140 offset:0
	ds_write_b32 v123, v141 offset:4
	ds_write_b32 v123, v142 offset:8
	ds_write_b32 v123, v143 offset:12
	ds_write_b32 v123, v150 offset:8320
	ds_write_b32 v123, v151 offset:8324
	ds_write_b32 v123, v152 offset:8328
	ds_write_b32 v123, v153 offset:8332
	s_waitcnt lgkmcnt(0)
	s_barrier
	s_mov_b64 s[26:27], s[16:17]
	s_add_i32 s4, s2, 896
	s_cmpk_lt_u32 s4, 0x200
	s_cselect_b32 s6, s28, s30
	s_cselect_b32 s7, s29, s31
	s_mov_b32 s16, 0x10500000
	s_cselect_b32 s16, 0x10100000, s16
	s_bfe_u32 s5, s4, 0x10008
	s_lshl_b32 s3, s5, 22
	s_add_u32 s6, s6, s3
	s_addc_u32 s7, s7, 0
	s_lshl_b32 s3, s5, 21
	s_add_i32 s16, s16, s3
	s_and_b32 s3, s4, 15
	s_bfe_u32 s5, s4, 0x40004
	s_lshl_b32 s17, s3, 18
	s_lshl_b32 s20, s5, 8
	s_add_i32 s17, s17, s20
	s_add_u32 s6, s6, s17
	s_addc_u32 s7, s7, 0
	s_add_u32 s12, s6, 0x20000
	s_addc_u32 s13, s7, 0
	s_lshl_b32 s17, s5, 17
	s_lshl_b32 s20, s3, 7
	s_add_i32 s17, s17, s20
	s_add_i32 s16, s16, s17
	s_add_u32 s16, s96, s16
	s_addc_u32 s17, s97, 0
	global_load_dwordx4 v[140:143], v122, s[6:7]
	global_load_dwordx4 v[150:153], v122, s[12:13]
	ds_read_b32 v154, v136 offset:0
	ds_read_b32 v155, v136 offset:260
	ds_read_b32 v156, v136 offset:520
	ds_read_b32 v157, v136 offset:780
	ds_read_b32 v158, v136 offset:1040
	ds_read_b32 v159, v136 offset:1300
	ds_read_b32 v160, v136 offset:1560
	ds_read_b32 v161, v136 offset:1820
	s_waitcnt lgkmcnt(0)
	v_cvt_pk_bf16_f32 v204, v154, v155
	v_cvt_pk_bf16_f32 v205, v156, v157
	v_cvt_pk_bf16_f32 v206, v158, v159
	v_cvt_pk_bf16_f32 v207, v160, v161
	global_store_dwordx4 v137, v[204:207], s[26:27]
	s_barrier
	s_waitcnt vmcnt(0)
	ds_write_b32 v123, v140 offset:0
	ds_write_b32 v123, v141 offset:4
	ds_write_b32 v123, v142 offset:8
	ds_write_b32 v123, v143 offset:12
	ds_write_b32 v123, v150 offset:8320
	ds_write_b32 v123, v151 offset:8324
	ds_write_b32 v123, v152 offset:8328
	ds_write_b32 v123, v153 offset:8332
	s_waitcnt lgkmcnt(0)
	s_barrier
	s_mov_b64 s[26:27], s[16:17]
	ds_read_b32 v154, v136 offset:0
	ds_read_b32 v155, v136 offset:260
	ds_read_b32 v156, v136 offset:520
	ds_read_b32 v157, v136 offset:780
	ds_read_b32 v158, v136 offset:1040
	ds_read_b32 v159, v136 offset:1300
	ds_read_b32 v160, v136 offset:1560
	ds_read_b32 v161, v136 offset:1820
	s_waitcnt lgkmcnt(0)
	v_cvt_pk_bf16_f32 v204, v154, v155
	v_cvt_pk_bf16_f32 v205, v156, v157
	v_cvt_pk_bf16_f32 v206, v158, v159
	v_cvt_pk_bf16_f32 v207, v160, v161
	global_store_dwordx4 v137, v[204:207], s[26:27]
	s_barrier
	s_branch .LBB0_243
